# stack on top of slimmed NSA issue-loop control: steady-state vmcnt fast path for the sel-loop header and the retention loops, rescale block moved out of line
# baseline (speedup 1.0000x reference)
; #define VWAIT(n) asm volatile("s_waitcnt vmcnt(" #n ")" ::: "memory")
; DI void ring_wait3(int rem) {
;   if (rem >= 3) VWAIT(9); else if (rem == 2) VWAIT(6); else if (rem == 1) VWAIT(3); else VWAIT(0);
; }
.LBB0_464:
	s_xor_b32 s12, s13, -2
	s_add_i32 s12, s12, s42
	s_mov_b32 s28, s6
	s_cmp_lg_u32 s12, 1
	s_cbranch_scc1 .Lrt_slow0
	s_waitcnt vmcnt(3)

; #define VWAIT(n) asm volatile("s_waitcnt vmcnt(" #n ")" ::: "memory")
; DI void ring_wait3(int rem) {
;   if (rem >= 3) VWAIT(9); else if (rem == 2) VWAIT(6); else if (rem == 1) VWAIT(3); else VWAIT(0);
; }
.LBB0_484:
	s_sub_i32 s14, s42, s13
	s_add_i32 s6, s14, -3
	s_cmp_lg_u32 s14, 4
	s_cbranch_scc1 .Lrt_slow1
	s_waitcnt vmcnt(3)

; #define VWAIT(n) asm volatile("s_waitcnt vmcnt(" #n ")" ::: "memory")
; DI void ring_wait3(int rem) {
;   if (rem >= 3) VWAIT(9); else if (rem == 2) VWAIT(6); else if (rem == 1) VWAIT(3); else VWAIT(0);
; }
.Lrt_slow0:
	s_cmp_lt_i32 s12, 3
	s_mov_b64 s[6:7], -1
	s_cbranch_scc0 .LBB0_473
	s_cmp_gt_i32 s12, 1
	s_cbranch_scc0 .LBB0_467
	s_waitcnt vmcnt(6)
	s_mov_b64 s[6:7], 0

; #define VWAIT(n) asm volatile("s_waitcnt vmcnt(" #n ")" ::: "memory")
; DI void ring_wait3(int rem) {
;   if (rem >= 3) VWAIT(9); else if (rem == 2) VWAIT(6); else if (rem == 1) VWAIT(3); else VWAIT(0);
; }
.LBB0_473:
	s_and_b64 vcc, exec, s[6:7]
	s_cbranch_vccz .LBB0_475
	s_waitcnt vmcnt(9)
	s_branch .LBB0_475
.Lrt_slow1:
	s_cmp_lt_i32 s6, 3
	s_mov_b64 s[6:7], -1
	s_cbranch_scc0 .LBB0_493
	s_cmp_gt_i32 s14, 4
	s_cbranch_scc0 .LBB0_487
	s_waitcnt vmcnt(6)
	s_mov_b64 s[6:7], 0

; #define VWAIT(n) asm volatile("s_waitcnt vmcnt(" #n ")" ::: "memory")
; DI void ring_wait3(int rem) {
;   if (rem >= 3) VWAIT(9); else if (rem == 2) VWAIT(6); else if (rem == 1) VWAIT(3); else VWAIT(0);
; }
.Lrt_slow2:
	s_cmp_lt_i32 s13, 3
	s_mov_b64 s[6:7], -1
	s_cbranch_scc0 .LBB0_517
	s_cmp_gt_i32 s13, 1
	s_cbranch_scc0 .LBB0_511
	s_waitcnt vmcnt(6)
	s_mov_b64 s[6:7], 0

; #define VWAIT(n) asm volatile("s_waitcnt vmcnt(" #n ")" ::: "memory")
; DI void ring_wait3(int rem) {
;   if (rem >= 3) VWAIT(9); else if (rem == 2) VWAIT(6); else if (rem == 1) VWAIT(3); else VWAIT(0);
; }
; DI void ret_unit(const Params& p, int b, int hr, int tq, char* smem) {
;     ...
;   if (kt + 1 < ntile) { RET_BODY(c0, c1, x0, x1); c0 = x0; c1 = x1; ++kt; }
.LBB0_507:
	s_or_b32 s12, s28, 1
	v_lshlrev_b32_e32 v208, 3, v208
	v_and_b32_e32 v214, 15, v1
	v_bfe_u32 v200, v1, 4, 2
	s_cmp_ge_i32 s12, s43
	s_cbranch_scc1 .LBB0_529
	s_xor_b32 s13, s28, -2
	s_add_i32 s13, s13, s42
	s_cmp_lg_u32 s13, 1
	s_cbranch_scc1 .Lrt_slow2
	s_waitcnt vmcnt(3)

; #define VWAIT(n) asm volatile("s_waitcnt vmcnt(" #n ")" ::: "memory")
; DI void ring_wait4(int rem) {
;   if (rem >= 3) VWAIT(12); else if (rem == 2) VWAIT(8); else if (rem == 1) VWAIT(4); else VWAIT(0);
; }
.LBB0_586:
	s_xor_b32 s26, s22, -2
	s_add_i32 s26, s26, s23
	s_cmp_lg_u32 s26, 1
	s_cbranch_scc1 .Lvm_slowH
	s_waitcnt vmcnt(4)

; DI float fexp2(float x) { return __builtin_amdgcn_exp2f(x); }
; #define VWAIT(n) asm volatile("s_waitcnt vmcnt(" #n ")" ::: "memory")
; DI void osm_decide(float pmn, float& m, float& l, f32x16 (&o)[4]) {
;   if (!__all(pmn - m <= THR)) {
;     float mn = fmaxf(m, pmn); float alpha = fexp2(m - mn); m = mn; l *= alpha;
; #pragma unroll
;     for (int d = 0; d < 4; ++d)
; #pragma unroll
;       for (int r = 0; r < 16; ++r) o[d][r] *= alpha;
;   }
; }
; DI void ring_wait4(int rem) {
;   if (rem >= 3) VWAIT(12); else if (rem == 2) VWAIT(8); else if (rem == 1) VWAIT(4); else VWAIT(0);
; }
.Lresc0:
	v_max_f32_e32 v66, v66, v66
	v_max_f32_e32 v67, v194, v194
	v_max_f32_e32 v67, v67, v66
	v_sub_f32_e32 v66, v194, v67
	v_exp_f32_e32 v66, v66
	v_mov_b32_e32 v194, v67
	v_mul_f32_e32 v195, v195, v66
	v_pk_mul_f32 v[64:65], v[64:65], v[66:67] op_sel_hi:[1,0]
	v_pk_mul_f32 v[62:63], v[62:63], v[66:67] op_sel_hi:[1,0]
	v_pk_mul_f32 v[60:61], v[60:61], v[66:67] op_sel_hi:[1,0]
	v_pk_mul_f32 v[58:59], v[58:59], v[66:67] op_sel_hi:[1,0]
	v_pk_mul_f32 v[56:57], v[56:57], v[66:67] op_sel_hi:[1,0]
	v_pk_mul_f32 v[54:55], v[54:55], v[66:67] op_sel_hi:[1,0]
	v_pk_mul_f32 v[52:53], v[52:53], v[66:67] op_sel_hi:[1,0]
	v_pk_mul_f32 v[50:51], v[50:51], v[66:67] op_sel_hi:[1,0]
	v_pk_mul_f32 v[48:49], v[48:49], v[66:67] op_sel_hi:[1,0]
	v_pk_mul_f32 v[46:47], v[46:47], v[66:67] op_sel_hi:[1,0]
	v_pk_mul_f32 v[44:45], v[44:45], v[66:67] op_sel_hi:[1,0]
	v_pk_mul_f32 v[42:43], v[42:43], v[66:67] op_sel_hi:[1,0]
	v_pk_mul_f32 v[40:41], v[40:41], v[66:67] op_sel_hi:[1,0]
	v_pk_mul_f32 v[38:39], v[38:39], v[66:67] op_sel_hi:[1,0]
	v_pk_mul_f32 v[36:37], v[36:37], v[66:67] op_sel_hi:[1,0]
	v_pk_mul_f32 v[34:35], v[34:35], v[66:67] op_sel_hi:[1,0]
	v_pk_mul_f32 v[32:33], v[32:33], v[66:67] op_sel_hi:[1,0]
	v_pk_mul_f32 v[30:31], v[30:31], v[66:67] op_sel_hi:[1,0]
	v_pk_mul_f32 v[28:29], v[28:29], v[66:67] op_sel_hi:[1,0]
	v_pk_mul_f32 v[26:27], v[26:27], v[66:67] op_sel_hi:[1,0]
	v_pk_mul_f32 v[24:25], v[24:25], v[66:67] op_sel_hi:[1,0]
	v_pk_mul_f32 v[22:23], v[22:23], v[66:67] op_sel_hi:[1,0]
	v_pk_mul_f32 v[20:21], v[20:21], v[66:67] op_sel_hi:[1,0]
	v_pk_mul_f32 v[18:19], v[18:19], v[66:67] op_sel_hi:[1,0]
	v_pk_mul_f32 v[16:17], v[16:17], v[66:67] op_sel_hi:[1,0]
	v_pk_mul_f32 v[14:15], v[14:15], v[66:67] op_sel_hi:[1,0]
	v_pk_mul_f32 v[12:13], v[12:13], v[66:67] op_sel_hi:[1,0]
	v_pk_mul_f32 v[10:11], v[10:11], v[66:67] op_sel_hi:[1,0]
	v_pk_mul_f32 v[8:9], v[8:9], v[66:67] op_sel_hi:[1,0]
	v_pk_mul_f32 v[6:7], v[6:7], v[66:67] op_sel_hi:[1,0]
	v_pk_mul_f32 v[4:5], v[4:5], v[66:67] op_sel_hi:[1,0]
	v_pk_mul_f32 v[2:3], v[2:3], v[66:67] op_sel_hi:[1,0]
	s_branch .LBB0_614
.Lvm_slowH:
	s_cmp_lt_i32 s26, 3
	s_mov_b64 s[4:5], -1
	s_cbranch_scc0 .LBB0_598
	s_mov_b64 s[8:9], -1
	s_mov_b64 s[4:5], 0
	s_cmp_lt_i32 s26, 2
	s_mov_b64 s[6:7], 0
	s_cbranch_scc1 .LBB0_593
	s_cmp_eq_u32 s26, 2
	s_mov_b64 s[6:7], -1
	s_cbranch_scc0 .LBB0_590
	s_waitcnt vmcnt(8)
	s_mov_b64 s[6:7], 0

; #define VWAIT(n) asm volatile("s_waitcnt vmcnt(" #n ")" ::: "memory")
; DI void ring_wait4(int rem) {
;   if (rem >= 3) VWAIT(12); else if (rem == 2) VWAIT(8); else if (rem == 1) VWAIT(4); else VWAIT(0);
; }
.LBB0_598:
	s_and_b64 vcc, exec, s[4:5]
	s_cbranch_vccz .LBB0_600
	s_waitcnt vmcnt(12)
	s_branch .LBB0_600
.Lmore0:
	s_cmp_lt_i32 s8, s12
	s_cbranch_scc0 .LBB0_612
	s_sub_i32 s7, s7, 64
	s_sub_i32 s9, s9, 64
	s_addk_i32 s26, 0x4000
	s_add_i32 s27, s27, 0x8000
	s_branch .LBB0_602

; #define MFMA(a, b, c) __builtin_amdgcn_mfma_f32_32x32x16_f16((a), (b), (c), 0, 0, 0)
; #define QK_LD(dst, s0) do { dst[0] = *(const f16x8*)(Kst + kbe + 512 * ((s0) >> 1)); dst[1] = *(const f16x8*)(Kst + kbe + 512 * ((s0) >> 1) + 8192); \
;     dst[2] = *(const f16x8*)(Kst + kbo + 512 * ((s0) >> 1)); dst[3] = *(const f16x8*)(Kst + kbo + 512 * ((s0) >> 1) + 8192); } while (0)
; #define QK_LD(dst, s0) do { dst[0] = *(const f16x8*)(Kst + kbe + 512 * ((s0) >> 1)); dst[1] = *(const f16x8*)(Kst + kbe + 512 * ((s0) >> 1) + 8192); \
;     dst[2] = *(const f16x8*)(Kst + kbo + 512 * ((s0) >> 1)); dst[3] = *(const f16x8*)(Kst + kbo + 512 * ((s0) >> 1) + 8192); } while (0)
; #define EXP8(c, b0) do { _Pragma("unroll") for (int j_ = 0; j_ < 8; ++j_) { c[(b0) + j_] = fexp2(c[(b0) + j_] - me); s_ += c[(b0) + j_]; } } while (0)
; DI void qk_exp(f32x16& n0, f32x16& n1, const char* Kst, const f16x8 (&qf)[8], unsigned kbe, unsigned kbo, f32x16& c0, f32x16& c1, float me, float& ps) {
;   const f32x16 zero = {0.f, 0.f, 0.f, 0.f, 0.f, 0.f, 0.f, 0.f, 0.f, 0.f, 0.f, 0.f, 0.f, 0.f, 0.f, 0.f};
;   f16x8 ka[4], kb[4];
;     ...
;   float s_ = 0.f;
;   QK_LD(ka, 0);
;   n0 = MFMA(ka[0], qf[0], zero); n1 = MFMA(ka[1], qf[0], zero); n0 = MFMA(ka[2], qf[1], n0); n1 = MFMA(ka[3], qf[1], n1);
;   QK_LD(kb, 2);
;   EXP8(c0, 0);
;   n0 = MFMA(kb[0], qf[2], n0); n1 = MFMA(kb[1], qf[2], n1); n0 = MFMA(kb[2], qf[3], n0); n1 = MFMA(kb[3], qf[3], n1);
;   QK_LD(ka, 4);
;   EXP8(c0, 8);
;   n0 = MFMA(ka[0], qf[4], n0); n1 = MFMA(ka[1], qf[4], n1); n0 = MFMA(ka[2], qf[5], n0); n1 = MFMA(ka[3], qf[5], n1);
;   QK_LD(kb, 6);
;   EXP8(c1, 0);
;   n0 = MFMA(kb[0], qf[6], n0); n1 = MFMA(kb[1], qf[6], n1); n0 = MFMA(kb[2], qf[7], n0); n1 = MFMA(kb[3], qf[7], n1);
;   EXP8(c1, 8);
;   ps = s_;
;     ...
; }
.LBB0_612:
	v_cndmask_b32_e64 v204, v233, v194, s[0:1]
	s_lshl_b32 s0, s25, 15
	s_and_b32 s7, s0, 0x18000
	s_waitcnt lgkmcnt(0)
	v_mfma_f32_32x32x16_f16 v[114:129], v[98:101], v[150:153], 0
	v_sub_f32_e32 v82, v82, v204
	v_exp_f32_e32 v217, v82
	v_sub_f32_e32 v83, v83, v204
	v_exp_f32_e32 v218, v83
	v_sub_f32_e32 v83, v84, v204
	v_exp_f32_e32 v219, v83
	v_sub_f32_e32 v83, v85, v204
	v_mfma_f32_32x32x16_f16 v[98:113], v[102:105], v[150:153], 0
	v_exp_f32_e32 v220, v83
	v_sub_f32_e32 v83, v86, v204
	v_add_f32_e32 v82, 0, v217
	v_exp_f32_e32 v221, v83
	v_sub_f32_e32 v83, v87, v204
	v_add_f32_e32 v82, v218, v82
	v_exp_f32_e32 v224, v83
	v_mfma_f32_32x32x16_f16 v[114:129], v[196:199], v[158:161], v[114:129]
	v_sub_f32_e32 v83, v88, v204
	v_add_f32_e32 v82, v219, v82
	v_exp_f32_e32 v225, v83
	v_sub_f32_e32 v83, v89, v204
	v_add_f32_e32 v82, v220, v82
	v_exp_f32_e32 v226, v83
	v_add_f32_e32 v82, v221, v82
	v_mfma_f32_32x32x16_f16 v[98:113], v[200:203], v[158:161], v[98:113]
	ds_read_b128 v[196:199], v205 offset:512
	ds_read_b128 v[200:203], v205 offset:8704
	ds_read_b128 v[208:211], v216 offset:512
	ds_read_b128 v[212:215], v216 offset:8704
	v_add_f32_e32 v82, v224, v82
	v_add_f32_e32 v82, v225, v82
	v_add_f32_e32 v227, v226, v82
	v_sub_f32_e32 v90, v90, v204
	v_sub_f32_e32 v91, v91, v204
	v_sub_f32_e32 v66, v66, v204
	s_waitcnt lgkmcnt(0)
	v_mfma_f32_32x32x16_f16 v[114:129], v[196:199], v[142:145], v[114:129]
	v_sub_f32_e32 v67, v67, v204
	s_lshl_b32 s0, s22, 15
	s_and_b32 s9, s0, 0x10000
	v_mfma_f32_32x32x16_f16 v[98:113], v[200:203], v[142:145], v[98:113]
	ds_read_b128 v[82:85], v205 offset:1024
	ds_read_b128 v[86:89], v205 offset:9216
	ds_read_b128 v[196:199], v216 offset:1024
	ds_read_b128 v[200:203], v216 offset:9216
	v_mfma_f32_32x32x16_f16 v[114:129], v[208:211], v[154:157], v[114:129]
	v_exp_f32_e32 v208, v90
	v_exp_f32_e32 v209, v91
	v_sub_f32_e32 v91, v92, v204
	v_exp_f32_e32 v210, v91
	v_sub_f32_e32 v91, v93, v204
	v_exp_f32_e32 v211, v91
	v_sub_f32_e32 v91, v94, v204
	v_mfma_f32_32x32x16_f16 v[98:113], v[212:215], v[154:157], v[98:113]
	v_add_f32_e32 v90, v208, v227
	v_exp_f32_e32 v212, v91
	v_sub_f32_e32 v91, v95, v204
	v_add_f32_e32 v90, v209, v90
	v_exp_f32_e32 v213, v91
	v_sub_f32_e32 v91, v96, v204
	v_add_f32_e32 v90, v210, v90
	s_waitcnt lgkmcnt(0)
	v_mfma_f32_32x32x16_f16 v[114:129], v[82:85], v[138:141], v[114:129]
	v_exp_f32_e32 v214, v91
	v_sub_f32_e32 v91, v97, v204
	v_add_f32_e32 v90, v211, v90
	v_exp_f32_e32 v215, v91
	v_add_f32_e32 v90, v212, v90
	v_add_f32_e32 v90, v213, v90
	v_add_f32_e32 v90, v214, v90
	v_mfma_f32_32x32x16_f16 v[98:113], v[86:89], v[138:141], v[98:113]
	v_add_f32_e32 v227, v215, v90
	ds_read_b128 v[82:85], v205 offset:1536
	ds_read_b128 v[86:89], v205 offset:9728
	ds_read_b128 v[90:93], v216 offset:1536
	ds_read_b128 v[94:97], v216 offset:9728
	v_add_u32_e32 v205, s9, v192
	v_mfma_f32_32x32x16_f16 v[114:129], v[196:199], v[146:149], v[114:129]
	v_exp_f32_e32 v196, v66
	v_exp_f32_e32 v197, v67
	v_sub_f32_e32 v67, v68, v204
	v_exp_f32_e32 v198, v67
	v_sub_f32_e32 v67, v69, v204
	v_exp_f32_e32 v199, v67
	v_sub_f32_e32 v67, v70, v204
	v_mfma_f32_32x32x16_f16 v[98:113], v[200:203], v[146:149], v[98:113]
	v_add_f32_e32 v66, v196, v227
	v_exp_f32_e32 v200, v67
	v_sub_f32_e32 v67, v71, v204
	v_add_f32_e32 v66, v197, v66
	v_exp_f32_e32 v201, v67
	v_sub_f32_e32 v67, v72, v204
	v_add_f32_e32 v66, v198, v66
	s_waitcnt lgkmcnt(0)
	v_mfma_f32_32x32x16_f16 v[114:129], v[82:85], v[130:133], v[114:129]
	v_exp_f32_e32 v202, v67
	v_sub_f32_e32 v67, v73, v204
	v_add_f32_e32 v66, v199, v66
	v_exp_f32_e32 v203, v67
	v_sub_f32_e32 v67, v74, v204
	v_add_f32_e32 v66, v200, v66
	v_add_f32_e32 v66, v201, v66
	v_mfma_f32_32x32x16_f16 v[98:113], v[86:89], v[130:133], v[98:113]
	v_exp_f32_e32 v86, v67
	v_sub_f32_e32 v67, v75, v204
	v_exp_f32_e32 v87, v67
	v_sub_f32_e32 v67, v76, v204
	v_add_f32_e32 v66, v202, v66
	v_exp_f32_e32 v88, v67
	v_sub_f32_e32 v67, v77, v204
	v_add_f32_e32 v66, v203, v66
	v_exp_f32_e32 v89, v67
	v_sub_f32_e32 v67, v78, v204
	v_mfma_f32_32x32x16_f16 v[114:129], v[90:93], v[134:137], v[114:129]
	v_add_f32_e32 v66, v86, v66
	v_exp_f32_e32 v90, v67
	v_sub_f32_e32 v67, v79, v204
	v_add_f32_e32 v66, v87, v66
	v_exp_f32_e32 v91, v67
	v_sub_f32_e32 v67, v80, v204
	v_add_f32_e32 v66, v88, v66
	v_exp_f32_e32 v92, v67
	v_sub_f32_e32 v67, v81, v204
	v_add_f32_e32 v66, v89, v66
	v_exp_f32_e32 v93, v67
	v_add_f32_e32 v66, v90, v66
	v_add_f32_e32 v66, v91, v66
	v_add_f32_e32 v66, v92, v66
	v_add_f32_e32 v66, v93, v66
	v_add_f32_e32 v195, v195, v66
	v_add_u32_e32 v204, s9, v1
	ds_read_b64_tr_b16 v[66:67], v204 offset:0
	ds_read_b64_tr_b16 v[68:69], v205 offset:0x800
	ds_read_b64_tr_b16 v[70:71], v204 offset:0x1000
	v_mfma_f32_32x32x16_f16 v[98:113], v[94:97], v[134:137], v[98:113]
	ds_read_b64_tr_b16 v[72:73], v205 offset:0x1800
	ds_read_b64_tr_b16 v[74:75], v204 offset:0x2000
	ds_read_b64_tr_b16 v[76:77], v205 offset:0x2800
	ds_read_b64_tr_b16 v[78:79], v204 offset:0x3000
	ds_read_b64_tr_b16 v[80:81], v205 offset:0x3800
	s_waitcnt lgkmcnt(0)
; #define SBAR() __builtin_amdgcn_sched_barrier(0)
; DI void pv_max(f32x16 (&o)[4], unsigned vb0, unsigned vb1, const f32x16& p0, const f32x16& p1, const f32x16& n0, const f32x16& n1, float& pm) {
;   f16x8 pb[4]; pb[0] = pack8(p0, 0); pb[1] = pack8(p0, 1); pb[2] = pack8(p1, 0); pb[3] = pack8(p1, 1);
;   VFrag fa;
;   float mx = n0[0];
;   pv_rd<0>(fa, vb0, vb1);
;   asm volatile("s_waitcnt lgkmcnt(0)" ::: "memory"); SBAR();
;   pv_mm(o[0], fa, pb);
;   pv_rd<1>(fa, vb0, vb1);
; #pragma unroll
;   for (int r = 1; r < 8; ++r) mx = fmaxf(mx, n0[r]);
;   asm volatile("s_waitcnt lgkmcnt(0)" ::: "memory"); SBAR();
;   pv_mm(o[1], fa, pb);
;   pv_rd<2>(fa, vb0, vb1);
; #pragma unroll
;   for (int r = 8; r < 16; ++r) mx = fmaxf(mx, n0[r]);
;   asm volatile("s_waitcnt lgkmcnt(0)" ::: "memory"); SBAR();
;   pv_mm(o[2], fa, pb);
;   pv_rd<3>(fa, vb0, vb1);
; #pragma unroll
;   for (int r = 0; r < 8; ++r) mx = fmaxf(mx, n1[r]);
;   asm volatile("s_waitcnt lgkmcnt(0)" ::: "memory"); SBAR();
;   pv_mm(o[3], fa, pb);
; #pragma unroll
;   for (int r = 8; r < 16; ++r) mx = fmaxf(mx, n1[r]);
;   pm = mx;
; }
	v_cvt_pk_f16_f32 v85, v225, v226
	v_cvt_pk_f16_f32 v84, v221, v224
	v_cvt_pk_f16_f32 v83, v219, v220
	v_cvt_pk_f16_f32 v82, v217, v218
	s_nop 1
	v_mfma_f32_32x32x16_f16 v[50:65], v[66:69], v[82:85], v[50:65]
	v_cvt_pk_f16_f32 v69, v214, v215
	v_cvt_pk_f16_f32 v68, v212, v213
	v_cvt_pk_f16_f32 v67, v210, v211
	v_cvt_pk_f16_f32 v66, v208, v209
	s_nop 1
	v_mfma_f32_32x32x16_f16 v[50:65], v[70:73], v[66:69], v[50:65]
	v_cvt_pk_f16_f32 v73, v202, v203
	v_cvt_pk_f16_f32 v72, v200, v201
	v_cvt_pk_f16_f32 v71, v198, v199
	v_cvt_pk_f16_f32 v70, v196, v197
	v_max_f32_e32 v196, v115, v115
	v_max_f32_e32 v197, v114, v114
	v_max_f32_e32 v196, v197, v196
	v_mfma_f32_32x32x16_f16 v[50:65], v[74:77], v[70:73], v[50:65]
	v_cvt_pk_f16_f32 v77, v92, v93
	v_cvt_pk_f16_f32 v76, v90, v91
	v_cvt_pk_f16_f32 v75, v88, v89
	v_cvt_pk_f16_f32 v74, v86, v87
	v_max3_f32 v196, v196, v116, v117
	v_max3_f32 v196, v196, v118, v119
	v_max3_f32 v196, v196, v120, v121
	v_mfma_f32_32x32x16_f16 v[50:65], v[78:81], v[74:77], v[50:65]
	ds_read_b64_tr_b16 v[78:79], v204 offset:0x200
	ds_read_b64_tr_b16 v[80:81], v205 offset:0xa00
	ds_read_b64_tr_b16 v[86:87], v204 offset:0x1200
	ds_read_b64_tr_b16 v[88:89], v205 offset:0x1a00
	ds_read_b64_tr_b16 v[90:91], v204 offset:0x2200
	ds_read_b64_tr_b16 v[92:93], v205 offset:0x2a00
	ds_read_b64_tr_b16 v[94:95], v204 offset:0x3200
	ds_read_b64_tr_b16 v[96:97], v205 offset:0x3a00
	s_waitcnt lgkmcnt(0)
	s_nop 0
	v_mfma_f32_32x32x16_f16 v[34:49], v[78:81], v[82:85], v[34:49]
	ds_read_b64_tr_b16 v[78:79], v204 offset:0x400
	ds_read_b64_tr_b16 v[80:81], v205 offset:0xc00
	v_max3_f32 v196, v196, v122, v123
	v_max3_f32 v196, v196, v124, v125
	v_max3_f32 v196, v196, v126, v127
	v_max3_f32 v196, v196, v128, v129
	v_mfma_f32_32x32x16_f16 v[34:49], v[86:89], v[66:69], v[34:49]
	ds_read_b64_tr_b16 v[86:87], v204 offset:0x1400
	ds_read_b64_tr_b16 v[88:89], v205 offset:0x1c00
	v_mfma_f32_32x32x16_f16 v[34:49], v[90:93], v[70:73], v[34:49]
	ds_read_b64_tr_b16 v[90:91], v204 offset:0x2400
	ds_read_b64_tr_b16 v[92:93], v205 offset:0x2c00
	v_mfma_f32_32x32x16_f16 v[34:49], v[94:97], v[74:77], v[34:49]
	ds_read_b64_tr_b16 v[94:95], v204 offset:0x3400
	ds_read_b64_tr_b16 v[96:97], v205 offset:0x3c00
	s_waitcnt lgkmcnt(0)
	v_mfma_f32_32x32x16_f16 v[18:33], v[78:81], v[82:85], v[18:33]
	ds_read_b64_tr_b16 v[78:79], v204 offset:0x600
	ds_read_b64_tr_b16 v[80:81], v205 offset:0xe00
	v_max3_f32 v196, v196, v98, v99
	v_max3_f32 v196, v196, v100, v101
	v_max3_f32 v196, v196, v102, v103
	v_max3_f32 v196, v196, v104, v105
	v_mfma_f32_32x32x16_f16 v[18:33], v[86:89], v[66:69], v[18:33]
	ds_read_b64_tr_b16 v[86:87], v204 offset:0x1600
	ds_read_b64_tr_b16 v[88:89], v205 offset:0x1e00
	v_mfma_f32_32x32x16_f16 v[18:33], v[90:93], v[70:73], v[18:33]
	ds_read_b64_tr_b16 v[90:91], v204 offset:0x2600
	ds_read_b64_tr_b16 v[92:93], v205 offset:0x2e00
	v_mfma_f32_32x32x16_f16 v[18:33], v[94:97], v[74:77], v[18:33]
	ds_read_b64_tr_b16 v[94:95], v204 offset:0x3600
	ds_read_b64_tr_b16 v[96:97], v205 offset:0x3e00
	s_waitcnt lgkmcnt(0)
	v_mfma_f32_32x32x16_f16 v[2:17], v[78:81], v[82:85], v[2:17]
	v_max3_f32 v78, v196, v106, v107
	v_max3_f32 v78, v78, v108, v109
	s_add_i32 s0, s24, s16
	v_mfma_f32_32x32x16_f16 v[2:17], v[86:89], v[66:69], v[2:17]
	v_max3_f32 v66, v78, v110, v111
	v_max3_f32 v66, v66, v112, v113
	v_mov_b32_e32 v68, v66
	s_nop 1
	v_permlane32_swap_b32_e32 v66, v68
	v_bfe_u32 v67, v193, s0, 1
	v_max_f32_e32 v68, v68, v68
	v_mfma_f32_32x32x16_f16 v[2:17], v[90:93], v[70:73], v[2:17]
	v_max_f32_e32 v66, v66, v66
	v_max_f32_e32 v66, v66, v68
	v_cmp_eq_u32_e64 s[0:1], 0, v67
	s_nop 1
	v_cndmask_b32_e64 v66, v66, v232, s[0:1]
	v_sub_f32_e32 v67, v66, v194
	v_mfma_f32_32x32x16_f16 v[2:17], v[94:97], v[74:77], v[2:17]
	v_cmp_ge_f32_e32 vcc, s73, v67
	s_cmp_eq_u64 vcc, exec
	s_cbranch_scc0 .Lresc0

; DI float fexp2(float x) { return __builtin_amdgcn_exp2f(x); }
; DI void osm_decide(float pmn, float& m, float& l, f32x16 (&o)[4]) {
;   if (!__all(pmn - m <= THR)) {
;     float mn = fmaxf(m, pmn); float alpha = fexp2(m - mn); m = mn; l *= alpha;
; #pragma unroll
;     for (int d = 0; d < 4; ++d)
; #pragma unroll
;       for (int r = 0; r < 16; ++r) o[d][r] *= alpha;
;   }
; }
.Lresc1:
	v_max_f32_e32 v98, v98, v98
	v_max_f32_e32 v99, v194, v194
	v_max_f32_e32 v99, v99, v98
	v_sub_f32_e32 v98, v194, v99
	v_exp_f32_e32 v98, v98
	v_mov_b32_e32 v194, v99
	v_mul_f32_e32 v195, v195, v98
	v_pk_mul_f32 v[64:65], v[64:65], v[98:99] op_sel_hi:[1,0]
	v_pk_mul_f32 v[62:63], v[62:63], v[98:99] op_sel_hi:[1,0]
	v_pk_mul_f32 v[60:61], v[60:61], v[98:99] op_sel_hi:[1,0]
	v_pk_mul_f32 v[58:59], v[58:59], v[98:99] op_sel_hi:[1,0]
	v_pk_mul_f32 v[56:57], v[56:57], v[98:99] op_sel_hi:[1,0]
	v_pk_mul_f32 v[54:55], v[54:55], v[98:99] op_sel_hi:[1,0]
	v_pk_mul_f32 v[52:53], v[52:53], v[98:99] op_sel_hi:[1,0]
	v_pk_mul_f32 v[50:51], v[50:51], v[98:99] op_sel_hi:[1,0]
	v_pk_mul_f32 v[48:49], v[48:49], v[98:99] op_sel_hi:[1,0]
	v_pk_mul_f32 v[46:47], v[46:47], v[98:99] op_sel_hi:[1,0]
	v_pk_mul_f32 v[44:45], v[44:45], v[98:99] op_sel_hi:[1,0]
	v_pk_mul_f32 v[42:43], v[42:43], v[98:99] op_sel_hi:[1,0]
	v_pk_mul_f32 v[40:41], v[40:41], v[98:99] op_sel_hi:[1,0]
	v_pk_mul_f32 v[38:39], v[38:39], v[98:99] op_sel_hi:[1,0]
	v_pk_mul_f32 v[36:37], v[36:37], v[98:99] op_sel_hi:[1,0]
	v_pk_mul_f32 v[34:35], v[34:35], v[98:99] op_sel_hi:[1,0]
	v_pk_mul_f32 v[32:33], v[32:33], v[98:99] op_sel_hi:[1,0]
	v_pk_mul_f32 v[30:31], v[30:31], v[98:99] op_sel_hi:[1,0]
	v_pk_mul_f32 v[28:29], v[28:29], v[98:99] op_sel_hi:[1,0]
	v_pk_mul_f32 v[26:27], v[26:27], v[98:99] op_sel_hi:[1,0]
	v_pk_mul_f32 v[24:25], v[24:25], v[98:99] op_sel_hi:[1,0]
	v_pk_mul_f32 v[22:23], v[22:23], v[98:99] op_sel_hi:[1,0]
	v_pk_mul_f32 v[20:21], v[20:21], v[98:99] op_sel_hi:[1,0]
	v_pk_mul_f32 v[18:19], v[18:19], v[98:99] op_sel_hi:[1,0]
	v_pk_mul_f32 v[16:17], v[16:17], v[98:99] op_sel_hi:[1,0]
	v_pk_mul_f32 v[14:15], v[14:15], v[98:99] op_sel_hi:[1,0]
	v_pk_mul_f32 v[12:13], v[12:13], v[98:99] op_sel_hi:[1,0]
	v_pk_mul_f32 v[10:11], v[10:11], v[98:99] op_sel_hi:[1,0]
	v_pk_mul_f32 v[8:9], v[8:9], v[98:99] op_sel_hi:[1,0]
	v_pk_mul_f32 v[6:7], v[6:7], v[98:99] op_sel_hi:[1,0]
	v_pk_mul_f32 v[4:5], v[4:5], v[98:99] op_sel_hi:[1,0]
	v_pk_mul_f32 v[2:3], v[2:3], v[98:99] op_sel_hi:[1,0]
	s_branch .LBB0_639

; #define MFMA(a, b, c) __builtin_amdgcn_mfma_f32_32x32x16_f16((a), (b), (c), 0, 0, 0)
; #define QK_LD(dst, s0) do { dst[0] = *(const f16x8*)(Kst + kbe + 512 * ((s0) >> 1)); dst[1] = *(const f16x8*)(Kst + kbe + 512 * ((s0) >> 1) + 8192); \
;     dst[2] = *(const f16x8*)(Kst + kbo + 512 * ((s0) >> 1)); dst[3] = *(const f16x8*)(Kst + kbo + 512 * ((s0) >> 1) + 8192); } while (0)
; #define QK_LD(dst, s0) do { dst[0] = *(const f16x8*)(Kst + kbe + 512 * ((s0) >> 1)); dst[1] = *(const f16x8*)(Kst + kbe + 512 * ((s0) >> 1) + 8192); \
;     dst[2] = *(const f16x8*)(Kst + kbo + 512 * ((s0) >> 1)); dst[3] = *(const f16x8*)(Kst + kbo + 512 * ((s0) >> 1) + 8192); } while (0)
; #define EXP8(c, b0) do { _Pragma("unroll") for (int j_ = 0; j_ < 8; ++j_) { c[(b0) + j_] = fexp2(c[(b0) + j_] - me); s_ += c[(b0) + j_]; } } while (0)
; DI void qk_exp(f32x16& n0, f32x16& n1, const char* Kst, const f16x8 (&qf)[8], unsigned kbe, unsigned kbo, f32x16& c0, f32x16& c1, float me, float& ps) {
;   const f32x16 zero = {0.f, 0.f, 0.f, 0.f, 0.f, 0.f, 0.f, 0.f, 0.f, 0.f, 0.f, 0.f, 0.f, 0.f, 0.f, 0.f};
;   f16x8 ka[4], kb[4];
;     ...
;   float s_ = 0.f;
;   QK_LD(ka, 0);
;   n0 = MFMA(ka[0], qf[0], zero); n1 = MFMA(ka[1], qf[0], zero); n0 = MFMA(ka[2], qf[1], n0); n1 = MFMA(ka[3], qf[1], n1);
;   QK_LD(kb, 2);
;   EXP8(c0, 0);
;   n0 = MFMA(kb[0], qf[2], n0); n1 = MFMA(kb[1], qf[2], n1); n0 = MFMA(kb[2], qf[3], n0); n1 = MFMA(kb[3], qf[3], n1);
;   QK_LD(ka, 4);
;   EXP8(c0, 8);
;   n0 = MFMA(ka[0], qf[4], n0); n1 = MFMA(ka[1], qf[4], n1); n0 = MFMA(ka[2], qf[5], n0); n1 = MFMA(ka[3], qf[5], n1);
;   QK_LD(kb, 6);
;   EXP8(c1, 0);
;   n0 = MFMA(kb[0], qf[6], n0); n1 = MFMA(kb[1], qf[6], n1); n0 = MFMA(kb[2], qf[7], n0); n1 = MFMA(kb[3], qf[7], n1);
;   EXP8(c1, 8);
;   ps = s_;
;     ...
; }
.LBB0_637:
	v_cndmask_b32_e64 v204, v194, v233, s[0:1]
	s_waitcnt lgkmcnt(0)
	v_mfma_f32_32x32x16_f16 v[82:97], v[66:69], v[150:153], 0
	v_sub_f32_e32 v114, v114, v204
	v_exp_f32_e32 v217, v114
	v_sub_f32_e32 v115, v115, v204
	v_exp_f32_e32 v218, v115
	v_sub_f32_e32 v115, v116, v204
	v_exp_f32_e32 v219, v115
	v_sub_f32_e32 v115, v117, v204
	v_mfma_f32_32x32x16_f16 v[66:81], v[70:73], v[150:153], 0
	v_exp_f32_e32 v220, v115
	v_sub_f32_e32 v115, v118, v204
	v_add_f32_e32 v114, 0, v217
	v_exp_f32_e32 v221, v115
	v_sub_f32_e32 v115, v119, v204
	v_add_f32_e32 v114, v218, v114
	v_exp_f32_e32 v224, v115
	v_mfma_f32_32x32x16_f16 v[82:97], v[196:199], v[158:161], v[82:97]
	v_sub_f32_e32 v115, v120, v204
	v_add_f32_e32 v114, v219, v114
	v_exp_f32_e32 v225, v115
	v_sub_f32_e32 v115, v121, v204
	v_add_f32_e32 v114, v220, v114
	v_exp_f32_e32 v226, v115
	v_add_f32_e32 v114, v221, v114
	v_mfma_f32_32x32x16_f16 v[66:81], v[200:203], v[158:161], v[66:81]
	ds_read_b128 v[196:199], v205 offset:512
	ds_read_b128 v[200:203], v205 offset:8704
	ds_read_b128 v[208:211], v216 offset:512
	ds_read_b128 v[212:215], v216 offset:8704
	v_add_f32_e32 v114, v224, v114
	v_add_f32_e32 v114, v225, v114
	v_add_f32_e32 v227, v226, v114
	v_sub_f32_e32 v122, v122, v204
	v_sub_f32_e32 v123, v123, v204
	v_sub_f32_e32 v98, v98, v204
	s_waitcnt lgkmcnt(0)
	v_mfma_f32_32x32x16_f16 v[82:97], v[196:199], v[142:145], v[82:97]
	v_sub_f32_e32 v99, v99, v204
	v_mfma_f32_32x32x16_f16 v[66:81], v[200:203], v[142:145], v[66:81]
	ds_read_b128 v[114:117], v205 offset:1024
	ds_read_b128 v[118:121], v205 offset:9216
	ds_read_b128 v[196:199], v216 offset:1024
	ds_read_b128 v[200:203], v216 offset:9216
	v_mfma_f32_32x32x16_f16 v[82:97], v[208:211], v[154:157], v[82:97]
	v_exp_f32_e32 v208, v122
	v_exp_f32_e32 v209, v123
	v_sub_f32_e32 v123, v124, v204
	v_exp_f32_e32 v210, v123
	v_sub_f32_e32 v123, v125, v204
	v_exp_f32_e32 v211, v123
	v_sub_f32_e32 v123, v126, v204
	v_mfma_f32_32x32x16_f16 v[66:81], v[212:215], v[154:157], v[66:81]
	v_add_f32_e32 v122, v208, v227
	v_exp_f32_e32 v212, v123
	v_sub_f32_e32 v123, v127, v204
	v_add_f32_e32 v122, v209, v122
	v_exp_f32_e32 v213, v123
	v_sub_f32_e32 v123, v128, v204
	v_add_f32_e32 v122, v210, v122
	s_waitcnt lgkmcnt(0)
	v_mfma_f32_32x32x16_f16 v[82:97], v[114:117], v[138:141], v[82:97]
	v_exp_f32_e32 v214, v123
	v_sub_f32_e32 v123, v129, v204
	v_add_f32_e32 v122, v211, v122
	v_exp_f32_e32 v215, v123
	v_add_f32_e32 v122, v212, v122
	v_add_f32_e32 v122, v213, v122
	v_add_f32_e32 v122, v214, v122
	v_mfma_f32_32x32x16_f16 v[66:81], v[118:121], v[138:141], v[66:81]
	v_add_f32_e32 v227, v215, v122
	ds_read_b128 v[114:117], v205 offset:1536
	ds_read_b128 v[118:121], v205 offset:9728
	ds_read_b128 v[122:125], v216 offset:1536
	ds_read_b128 v[126:129], v216 offset:9728
	v_add_u32_e32 v205, s7, v192
	v_mfma_f32_32x32x16_f16 v[82:97], v[196:199], v[146:149], v[82:97]
	v_exp_f32_e32 v196, v98
	v_exp_f32_e32 v197, v99
	v_sub_f32_e32 v99, v100, v204
	v_exp_f32_e32 v198, v99
	v_sub_f32_e32 v99, v101, v204
	v_exp_f32_e32 v199, v99
	v_sub_f32_e32 v99, v102, v204
	v_mfma_f32_32x32x16_f16 v[66:81], v[200:203], v[146:149], v[66:81]
	v_add_f32_e32 v98, v196, v227
	v_exp_f32_e32 v200, v99
	v_sub_f32_e32 v99, v103, v204
	v_add_f32_e32 v98, v197, v98
	v_exp_f32_e32 v201, v99
	v_sub_f32_e32 v99, v104, v204
	v_add_f32_e32 v98, v198, v98
	s_waitcnt lgkmcnt(0)
	v_mfma_f32_32x32x16_f16 v[82:97], v[114:117], v[130:133], v[82:97]
	v_exp_f32_e32 v202, v99
	v_sub_f32_e32 v99, v105, v204
	v_add_f32_e32 v98, v199, v98
	v_exp_f32_e32 v203, v99
	v_sub_f32_e32 v99, v106, v204
	v_add_f32_e32 v98, v200, v98
	v_add_f32_e32 v98, v201, v98
	v_mfma_f32_32x32x16_f16 v[66:81], v[118:121], v[130:133], v[66:81]
	v_exp_f32_e32 v118, v99
	v_sub_f32_e32 v99, v107, v204
	v_exp_f32_e32 v119, v99
	v_sub_f32_e32 v99, v108, v204
	v_add_f32_e32 v98, v202, v98
	v_exp_f32_e32 v120, v99
	v_sub_f32_e32 v99, v109, v204
	v_add_f32_e32 v98, v203, v98
	v_exp_f32_e32 v121, v99
	v_sub_f32_e32 v99, v110, v204
	v_mfma_f32_32x32x16_f16 v[82:97], v[122:125], v[134:137], v[82:97]
	v_add_f32_e32 v98, v118, v98
	v_exp_f32_e32 v122, v99
	v_sub_f32_e32 v99, v111, v204
	v_add_f32_e32 v98, v119, v98
	v_exp_f32_e32 v123, v99
	v_sub_f32_e32 v99, v112, v204
	v_add_f32_e32 v98, v120, v98
	v_exp_f32_e32 v124, v99
	v_sub_f32_e32 v99, v113, v204
	v_add_f32_e32 v98, v121, v98
	v_exp_f32_e32 v125, v99
	v_add_f32_e32 v98, v122, v98
	v_add_f32_e32 v98, v123, v98
	v_add_f32_e32 v98, v124, v98
	v_add_f32_e32 v98, v125, v98
	v_add_f32_e32 v195, v195, v98
	v_add_u32_e32 v204, s7, v1
	ds_read_b64_tr_b16 v[98:99], v204 offset:0
	ds_read_b64_tr_b16 v[100:101], v205 offset:0x800
	ds_read_b64_tr_b16 v[102:103], v204 offset:0x1000
	v_mfma_f32_32x32x16_f16 v[66:81], v[126:129], v[134:137], v[66:81]
	ds_read_b64_tr_b16 v[104:105], v205 offset:0x1800
	ds_read_b64_tr_b16 v[106:107], v204 offset:0x2000
	ds_read_b64_tr_b16 v[108:109], v205 offset:0x2800
	ds_read_b64_tr_b16 v[110:111], v204 offset:0x3000
	ds_read_b64_tr_b16 v[112:113], v205 offset:0x3800
	s_waitcnt lgkmcnt(0)
; #define SBAR() __builtin_amdgcn_sched_barrier(0)
; DI void pv_max(f32x16 (&o)[4], unsigned vb0, unsigned vb1, const f32x16& p0, const f32x16& p1, const f32x16& n0, const f32x16& n1, float& pm) {
;   f16x8 pb[4]; pb[0] = pack8(p0, 0); pb[1] = pack8(p0, 1); pb[2] = pack8(p1, 0); pb[3] = pack8(p1, 1);
;   VFrag fa;
;   float mx = n0[0];
;   pv_rd<0>(fa, vb0, vb1);
;   asm volatile("s_waitcnt lgkmcnt(0)" ::: "memory"); SBAR();
;   pv_mm(o[0], fa, pb);
;   pv_rd<1>(fa, vb0, vb1);
; #pragma unroll
;   for (int r = 1; r < 8; ++r) mx = fmaxf(mx, n0[r]);
;   asm volatile("s_waitcnt lgkmcnt(0)" ::: "memory"); SBAR();
;   pv_mm(o[1], fa, pb);
;   pv_rd<2>(fa, vb0, vb1);
; #pragma unroll
;   for (int r = 8; r < 16; ++r) mx = fmaxf(mx, n0[r]);
;   asm volatile("s_waitcnt lgkmcnt(0)" ::: "memory"); SBAR();
;   pv_mm(o[2], fa, pb);
;   pv_rd<3>(fa, vb0, vb1);
; #pragma unroll
;   for (int r = 0; r < 8; ++r) mx = fmaxf(mx, n1[r]);
;   asm volatile("s_waitcnt lgkmcnt(0)" ::: "memory"); SBAR();
;   pv_mm(o[3], fa, pb);
; #pragma unroll
;   for (int r = 8; r < 16; ++r) mx = fmaxf(mx, n1[r]);
;   pm = mx;
; }
	v_cvt_pk_f16_f32 v117, v225, v226
	v_cvt_pk_f16_f32 v116, v221, v224
	v_cvt_pk_f16_f32 v115, v219, v220
	v_cvt_pk_f16_f32 v114, v217, v218
	s_nop 1
	v_mfma_f32_32x32x16_f16 v[50:65], v[98:101], v[114:117], v[50:65]
	v_cvt_pk_f16_f32 v101, v214, v215
	v_cvt_pk_f16_f32 v100, v212, v213
	v_cvt_pk_f16_f32 v99, v210, v211
	v_cvt_pk_f16_f32 v98, v208, v209
	s_nop 1
	v_mfma_f32_32x32x16_f16 v[50:65], v[102:105], v[98:101], v[50:65]
	v_cvt_pk_f16_f32 v105, v202, v203
	v_cvt_pk_f16_f32 v104, v200, v201
	v_cvt_pk_f16_f32 v103, v198, v199
	v_cvt_pk_f16_f32 v102, v196, v197
	v_max_f32_e32 v196, v83, v83
	v_max_f32_e32 v197, v82, v82
	v_max_f32_e32 v196, v197, v196
	v_mfma_f32_32x32x16_f16 v[50:65], v[106:109], v[102:105], v[50:65]
	v_cvt_pk_f16_f32 v109, v124, v125
	v_cvt_pk_f16_f32 v108, v122, v123
	v_cvt_pk_f16_f32 v107, v120, v121
	v_cvt_pk_f16_f32 v106, v118, v119
	v_max3_f32 v196, v196, v84, v85
	v_max3_f32 v196, v196, v86, v87
	v_max3_f32 v196, v196, v88, v89
	v_mfma_f32_32x32x16_f16 v[50:65], v[110:113], v[106:109], v[50:65]
	ds_read_b64_tr_b16 v[110:111], v204 offset:0x200
	ds_read_b64_tr_b16 v[112:113], v205 offset:0xa00
	ds_read_b64_tr_b16 v[118:119], v204 offset:0x1200
	ds_read_b64_tr_b16 v[120:121], v205 offset:0x1a00
	ds_read_b64_tr_b16 v[122:123], v204 offset:0x2200
	ds_read_b64_tr_b16 v[124:125], v205 offset:0x2a00
	ds_read_b64_tr_b16 v[126:127], v204 offset:0x3200
	ds_read_b64_tr_b16 v[128:129], v205 offset:0x3a00
	s_waitcnt lgkmcnt(0)
	s_nop 0
	v_mfma_f32_32x32x16_f16 v[34:49], v[110:113], v[114:117], v[34:49]
	ds_read_b64_tr_b16 v[110:111], v204 offset:0x400
	ds_read_b64_tr_b16 v[112:113], v205 offset:0xc00
	v_max3_f32 v196, v196, v90, v91
	v_max3_f32 v196, v196, v92, v93
	v_max3_f32 v196, v196, v94, v95
	v_max3_f32 v196, v196, v96, v97
	v_mfma_f32_32x32x16_f16 v[34:49], v[118:121], v[98:101], v[34:49]
	ds_read_b64_tr_b16 v[118:119], v204 offset:0x1400
	ds_read_b64_tr_b16 v[120:121], v205 offset:0x1c00
	v_mfma_f32_32x32x16_f16 v[34:49], v[122:125], v[102:105], v[34:49]
	ds_read_b64_tr_b16 v[122:123], v204 offset:0x2400
	ds_read_b64_tr_b16 v[124:125], v205 offset:0x2c00
	v_mfma_f32_32x32x16_f16 v[34:49], v[126:129], v[106:109], v[34:49]
	ds_read_b64_tr_b16 v[126:127], v204 offset:0x3400
	ds_read_b64_tr_b16 v[128:129], v205 offset:0x3c00
	s_waitcnt lgkmcnt(0)
	v_mfma_f32_32x32x16_f16 v[18:33], v[110:113], v[114:117], v[18:33]
	ds_read_b64_tr_b16 v[110:111], v204 offset:0x600
	ds_read_b64_tr_b16 v[112:113], v205 offset:0xe00
	v_max3_f32 v196, v196, v66, v67
	v_max3_f32 v196, v196, v68, v69
	v_max3_f32 v196, v196, v70, v71
	v_max3_f32 v196, v196, v72, v73
	v_mfma_f32_32x32x16_f16 v[18:33], v[118:121], v[98:101], v[18:33]
	ds_read_b64_tr_b16 v[118:119], v204 offset:0x1600
	ds_read_b64_tr_b16 v[120:121], v205 offset:0x1e00
	v_mfma_f32_32x32x16_f16 v[18:33], v[122:125], v[102:105], v[18:33]
	ds_read_b64_tr_b16 v[122:123], v204 offset:0x2600
	ds_read_b64_tr_b16 v[124:125], v205 offset:0x2e00
	v_mfma_f32_32x32x16_f16 v[18:33], v[126:129], v[106:109], v[18:33]
	ds_read_b64_tr_b16 v[126:127], v204 offset:0x3600
	ds_read_b64_tr_b16 v[128:129], v205 offset:0x3e00
	s_waitcnt lgkmcnt(0)
	v_mfma_f32_32x32x16_f16 v[2:17], v[110:113], v[114:117], v[2:17]
	v_max3_f32 v110, v196, v74, v75
	v_max3_f32 v110, v110, v76, v77
	v_max3_f32 v110, v110, v78, v79
	s_sub_i32 s0, s62, s22
	v_mfma_f32_32x32x16_f16 v[2:17], v[118:121], v[98:101], v[2:17]
	v_max3_f32 v98, v110, v80, v81
	v_mov_b32_e32 v100, v98
	v_lshrrev_b32_e32 v99, s0, v193
	s_nop 0
	v_permlane32_swap_b32_e32 v98, v100
	v_and_b32_e32 v99, 1, v99
	v_max_f32_e32 v100, v100, v100
	v_mfma_f32_32x32x16_f16 v[2:17], v[122:125], v[102:105], v[2:17]
	v_max_f32_e32 v98, v98, v98
	v_max_f32_e32 v98, v98, v100
	v_cmp_eq_u32_e64 s[0:1], 1, v99
	s_nop 1
	v_cndmask_b32_e64 v98, v232, v98, s[0:1]
	v_sub_f32_e32 v99, v98, v194
	v_mfma_f32_32x32x16_f16 v[2:17], v[126:129], v[106:109], v[2:17]
	v_cmp_ge_f32_e32 vcc, s73, v99
	s_cmp_eq_u64 vcc, exec
	s_cbranch_scc0 .Lresc1

; DI float fexp2(float x) { return __builtin_amdgcn_exp2f(x); }
; DI void osm_decide(float pmn, float& m, float& l, f32x16 (&o)[4]) {
;   if (!__all(pmn - m <= THR)) {
;     float mn = fmaxf(m, pmn); float alpha = fexp2(m - mn); m = mn; l *= alpha;
; #pragma unroll
;     for (int d = 0; d < 4; ++d)
; #pragma unroll
;       for (int r = 0; r < 16; ++r) o[d][r] *= alpha;
;   }
; }
.Lresc2:
	v_max_f32_e32 v66, v66, v66
	v_max_f32_e32 v67, v191, v191
	v_max_f32_e32 v67, v67, v66
	v_sub_f32_e32 v66, v191, v67
	v_exp_f32_e32 v66, v66
	v_mov_b32_e32 v191, v67
	v_mul_f32_e32 v193, v193, v66
	v_pk_mul_f32 v[64:65], v[64:65], v[66:67] op_sel_hi:[1,0]
	v_pk_mul_f32 v[62:63], v[62:63], v[66:67] op_sel_hi:[1,0]
	v_pk_mul_f32 v[60:61], v[60:61], v[66:67] op_sel_hi:[1,0]
	v_pk_mul_f32 v[58:59], v[58:59], v[66:67] op_sel_hi:[1,0]
	v_pk_mul_f32 v[56:57], v[56:57], v[66:67] op_sel_hi:[1,0]
	v_pk_mul_f32 v[54:55], v[54:55], v[66:67] op_sel_hi:[1,0]
	v_pk_mul_f32 v[52:53], v[52:53], v[66:67] op_sel_hi:[1,0]
	v_pk_mul_f32 v[50:51], v[50:51], v[66:67] op_sel_hi:[1,0]
	v_pk_mul_f32 v[48:49], v[48:49], v[66:67] op_sel_hi:[1,0]
	v_pk_mul_f32 v[46:47], v[46:47], v[66:67] op_sel_hi:[1,0]
	v_pk_mul_f32 v[44:45], v[44:45], v[66:67] op_sel_hi:[1,0]
	v_pk_mul_f32 v[42:43], v[42:43], v[66:67] op_sel_hi:[1,0]
	v_pk_mul_f32 v[40:41], v[40:41], v[66:67] op_sel_hi:[1,0]
	v_pk_mul_f32 v[38:39], v[38:39], v[66:67] op_sel_hi:[1,0]
	v_pk_mul_f32 v[36:37], v[36:37], v[66:67] op_sel_hi:[1,0]
	v_pk_mul_f32 v[34:35], v[34:35], v[66:67] op_sel_hi:[1,0]
	v_pk_mul_f32 v[32:33], v[32:33], v[66:67] op_sel_hi:[1,0]
	v_pk_mul_f32 v[30:31], v[30:31], v[66:67] op_sel_hi:[1,0]
	v_pk_mul_f32 v[28:29], v[28:29], v[66:67] op_sel_hi:[1,0]
	v_pk_mul_f32 v[26:27], v[26:27], v[66:67] op_sel_hi:[1,0]
	v_pk_mul_f32 v[24:25], v[24:25], v[66:67] op_sel_hi:[1,0]
	v_pk_mul_f32 v[22:23], v[22:23], v[66:67] op_sel_hi:[1,0]
	v_pk_mul_f32 v[20:21], v[20:21], v[66:67] op_sel_hi:[1,0]
	v_pk_mul_f32 v[18:19], v[18:19], v[66:67] op_sel_hi:[1,0]
	v_pk_mul_f32 v[16:17], v[16:17], v[66:67] op_sel_hi:[1,0]
	v_pk_mul_f32 v[14:15], v[14:15], v[66:67] op_sel_hi:[1,0]
	v_pk_mul_f32 v[12:13], v[12:13], v[66:67] op_sel_hi:[1,0]
	v_pk_mul_f32 v[10:11], v[10:11], v[66:67] op_sel_hi:[1,0]
	v_pk_mul_f32 v[8:9], v[8:9], v[66:67] op_sel_hi:[1,0]
	v_pk_mul_f32 v[6:7], v[6:7], v[66:67] op_sel_hi:[1,0]
	v_pk_mul_f32 v[4:5], v[4:5], v[66:67] op_sel_hi:[1,0]
	v_pk_mul_f32 v[2:3], v[2:3], v[66:67] op_sel_hi:[1,0]
	s_branch .LBB0_720

; #define MFMA(a, b, c) __builtin_amdgcn_mfma_f32_32x32x16_f16((a), (b), (c), 0, 0, 0)
; #define QK_LD(dst, s0) do { dst[0] = *(const f16x8*)(Kst + kbe + 512 * ((s0) >> 1)); dst[1] = *(const f16x8*)(Kst + kbe + 512 * ((s0) >> 1) + 8192); \
;     dst[2] = *(const f16x8*)(Kst + kbo + 512 * ((s0) >> 1)); dst[3] = *(const f16x8*)(Kst + kbo + 512 * ((s0) >> 1) + 8192); } while (0)
; #define QK_LD(dst, s0) do { dst[0] = *(const f16x8*)(Kst + kbe + 512 * ((s0) >> 1)); dst[1] = *(const f16x8*)(Kst + kbe + 512 * ((s0) >> 1) + 8192); \
;     dst[2] = *(const f16x8*)(Kst + kbo + 512 * ((s0) >> 1)); dst[3] = *(const f16x8*)(Kst + kbo + 512 * ((s0) >> 1) + 8192); } while (0)
; #define EXP8(c, b0) do { _Pragma("unroll") for (int j_ = 0; j_ < 8; ++j_) { c[(b0) + j_] = fexp2(c[(b0) + j_] - me); s_ += c[(b0) + j_]; } } while (0)
; DI void qk_exp(f32x16& n0, f32x16& n1, const char* Kst, const f16x8 (&qf)[8], unsigned kbe, unsigned kbo, f32x16& c0, f32x16& c1, float me, float& ps) {
;   const f32x16 zero = {0.f, 0.f, 0.f, 0.f, 0.f, 0.f, 0.f, 0.f, 0.f, 0.f, 0.f, 0.f, 0.f, 0.f, 0.f, 0.f};
;   f16x8 ka[4], kb[4];
;     ...
;   float s_ = 0.f;
;   QK_LD(ka, 0);
;   n0 = MFMA(ka[0], qf[0], zero); n1 = MFMA(ka[1], qf[0], zero); n0 = MFMA(ka[2], qf[1], n0); n1 = MFMA(ka[3], qf[1], n1);
;   QK_LD(kb, 2);
;   EXP8(c0, 0);
;   n0 = MFMA(kb[0], qf[2], n0); n1 = MFMA(kb[1], qf[2], n1); n0 = MFMA(kb[2], qf[3], n0); n1 = MFMA(kb[3], qf[3], n1);
;   QK_LD(ka, 4);
;   EXP8(c0, 8);
;   n0 = MFMA(ka[0], qf[4], n0); n1 = MFMA(ka[1], qf[4], n1); n0 = MFMA(ka[2], qf[5], n0); n1 = MFMA(ka[3], qf[5], n1);
;   QK_LD(kb, 6);
;   EXP8(c1, 0);
;   n0 = MFMA(kb[0], qf[6], n0); n1 = MFMA(kb[1], qf[6], n1); n0 = MFMA(kb[2], qf[7], n0); n1 = MFMA(kb[3], qf[7], n1);
;   EXP8(c1, 8);
;   ps = s_;
;     ...
; }
.LBB0_718:
	s_lshl_b32 s0, s19, 15
	s_and_b32 s19, s0, 0x18000
	v_sub_f32_e32 v66, v66, v191
	s_waitcnt lgkmcnt(0)
	v_mfma_f32_32x32x16_f16 v[114:129], v[98:101], v[150:153], 0
	v_exp_f32_e32 v214, v66
	v_sub_f32_e32 v67, v67, v191
	v_exp_f32_e32 v215, v67
	v_sub_f32_e32 v67, v68, v191
	v_exp_f32_e32 v216, v67
	v_sub_f32_e32 v67, v69, v191
	v_exp_f32_e32 v217, v67
	v_mfma_f32_32x32x16_f16 v[98:113], v[102:105], v[150:153], 0
	v_sub_f32_e32 v67, v70, v191
	v_add_f32_e32 v66, 0, v214
	v_exp_f32_e32 v218, v67
	v_sub_f32_e32 v67, v71, v191
	v_add_f32_e32 v66, v215, v66
	v_exp_f32_e32 v219, v67
	v_sub_f32_e32 v67, v72, v191
	v_mfma_f32_32x32x16_f16 v[114:129], v[194:197], v[158:161], v[114:129]
	v_add_f32_e32 v66, v216, v66
	v_exp_f32_e32 v220, v67
	v_sub_f32_e32 v67, v73, v191
	v_add_f32_e32 v66, v217, v66
	v_exp_f32_e32 v221, v67
	v_add_f32_e32 v66, v218, v66
	v_add_f32_e32 v66, v219, v66
	v_mfma_f32_32x32x16_f16 v[98:113], v[198:201], v[158:161], v[98:113]
	ds_read_b128 v[194:197], v212 offset:512
	ds_read_b128 v[198:201], v212 offset:8704
	ds_read_b128 v[202:205], v213 offset:512
	ds_read_b128 v[208:211], v213 offset:8704
	v_add_f32_e32 v66, v220, v66
	v_add_f32_e32 v224, v221, v66
	v_sub_f32_e32 v74, v74, v191
	v_sub_f32_e32 v75, v75, v191
	v_sub_f32_e32 v82, v82, v191
	v_sub_f32_e32 v83, v83, v191
	s_waitcnt lgkmcnt(0)
	v_mfma_f32_32x32x16_f16 v[114:129], v[194:197], v[142:145], v[114:129]
	s_lshl_b32 s0, s5, 15
	s_and_b32 s21, s0, 0x18000
	v_mfma_f32_32x32x16_f16 v[98:113], v[198:201], v[142:145], v[98:113]
	ds_read_b128 v[66:69], v212 offset:1024
	ds_read_b128 v[70:73], v212 offset:9216
	ds_read_b128 v[194:197], v213 offset:1024
	ds_read_b128 v[198:201], v213 offset:9216
	v_mfma_f32_32x32x16_f16 v[114:129], v[202:205], v[154:157], v[114:129]
	v_exp_f32_e32 v202, v74
	v_exp_f32_e32 v203, v75
	v_sub_f32_e32 v75, v76, v191
	v_exp_f32_e32 v204, v75
	v_sub_f32_e32 v75, v77, v191
	v_exp_f32_e32 v205, v75
	v_sub_f32_e32 v75, v78, v191
	v_mfma_f32_32x32x16_f16 v[98:113], v[208:211], v[154:157], v[98:113]
	v_add_f32_e32 v74, v202, v224
	v_exp_f32_e32 v208, v75
	v_sub_f32_e32 v75, v79, v191
	v_add_f32_e32 v74, v203, v74
	v_exp_f32_e32 v209, v75
	v_sub_f32_e32 v75, v80, v191
	v_add_f32_e32 v74, v204, v74
	s_waitcnt lgkmcnt(0)
	v_mfma_f32_32x32x16_f16 v[114:129], v[66:69], v[138:141], v[114:129]
	v_exp_f32_e32 v210, v75
	v_sub_f32_e32 v75, v81, v191
	v_add_f32_e32 v74, v205, v74
	v_exp_f32_e32 v211, v75
	v_add_f32_e32 v74, v208, v74
	v_add_f32_e32 v74, v209, v74
	v_add_f32_e32 v74, v210, v74
	v_mfma_f32_32x32x16_f16 v[98:113], v[70:73], v[138:141], v[98:113]
	v_add_f32_e32 v224, v211, v74
	ds_read_b128 v[66:69], v212 offset:1536
	ds_read_b128 v[70:73], v212 offset:9728
	ds_read_b128 v[74:77], v213 offset:1536
	ds_read_b128 v[78:81], v213 offset:9728
	v_mfma_f32_32x32x16_f16 v[114:129], v[194:197], v[146:149], v[114:129]
	v_exp_f32_e32 v194, v82
	v_exp_f32_e32 v195, v83
	v_sub_f32_e32 v83, v84, v191
	v_exp_f32_e32 v196, v83
	v_sub_f32_e32 v83, v85, v191
	v_exp_f32_e32 v197, v83
	v_sub_f32_e32 v83, v86, v191
	v_add_f32_e32 v82, v194, v224
	v_exp_f32_e32 v86, v83
	v_sub_f32_e32 v83, v87, v191
	v_add_f32_e32 v82, v195, v82
	v_exp_f32_e32 v87, v83
	v_sub_f32_e32 v83, v88, v191
	v_add_f32_e32 v82, v196, v82
	v_exp_f32_e32 v88, v83
	v_sub_f32_e32 v83, v89, v191
	v_mfma_f32_32x32x16_f16 v[98:113], v[198:201], v[146:149], v[98:113]
	v_add_f32_e32 v82, v197, v82
	v_exp_f32_e32 v89, v83
	v_add_f32_e32 v82, v86, v82
	v_add_f32_e32 v82, v87, v82
	v_add_f32_e32 v82, v88, v82
	v_add_f32_e32 v82, v89, v82
	v_add_u32_e32 v198, s21, v1
	s_waitcnt lgkmcnt(0)
	v_mfma_f32_32x32x16_f16 v[114:129], v[66:69], v[130:133], v[114:129]
	v_sub_f32_e32 v66, v90, v191
	v_exp_f32_e32 v90, v66
	v_sub_f32_e32 v67, v91, v191
	v_exp_f32_e32 v91, v67
	v_sub_f32_e32 v67, v92, v191
	v_exp_f32_e32 v92, v67
	v_sub_f32_e32 v67, v93, v191
	v_exp_f32_e32 v93, v67
	v_sub_f32_e32 v67, v94, v191
	v_add_f32_e32 v66, v90, v82
	v_exp_f32_e32 v94, v67
	v_sub_f32_e32 v67, v95, v191
	v_add_f32_e32 v66, v91, v66
	v_exp_f32_e32 v95, v67
	v_sub_f32_e32 v67, v96, v191
	v_add_f32_e32 v66, v92, v66
	v_exp_f32_e32 v96, v67
	v_sub_f32_e32 v67, v97, v191
	v_mfma_f32_32x32x16_f16 v[98:113], v[70:73], v[130:133], v[98:113]
	v_add_f32_e32 v66, v93, v66
	v_exp_f32_e32 v97, v67
	v_add_f32_e32 v66, v94, v66
	v_add_f32_e32 v66, v95, v66
	v_add_f32_e32 v66, v96, v66
	v_add_f32_e32 v66, v97, v66
	v_add_f32_e32 v193, v193, v66
	ds_read_b64_tr_b16 v[66:67], v198 offset:0
	v_add_u32_e32 v199, s21, v192
	ds_read_b64_tr_b16 v[68:69], v199 offset:0x800
	ds_read_b64_tr_b16 v[70:71], v198 offset:0x1000
	v_mfma_f32_32x32x16_f16 v[114:129], v[74:77], v[134:137], v[114:129]
	ds_read_b64_tr_b16 v[72:73], v199 offset:0x1800
	ds_read_b64_tr_b16 v[74:75], v198 offset:0x2000
	ds_read_b64_tr_b16 v[76:77], v199 offset:0x2800
	v_mfma_f32_32x32x16_f16 v[98:113], v[78:81], v[134:137], v[98:113]
	ds_read_b64_tr_b16 v[78:79], v198 offset:0x3000
	ds_read_b64_tr_b16 v[80:81], v199 offset:0x3800
	s_waitcnt lgkmcnt(0)
; #define SBAR() __builtin_amdgcn_sched_barrier(0)
; DI void pv_max(f32x16 (&o)[4], unsigned vb0, unsigned vb1, const f32x16& p0, const f32x16& p1, const f32x16& n0, const f32x16& n1, float& pm) {
;   f16x8 pb[4]; pb[0] = pack8(p0, 0); pb[1] = pack8(p0, 1); pb[2] = pack8(p1, 0); pb[3] = pack8(p1, 1);
;   VFrag fa;
;   float mx = n0[0];
;   pv_rd<0>(fa, vb0, vb1);
;   asm volatile("s_waitcnt lgkmcnt(0)" ::: "memory"); SBAR();
;   pv_mm(o[0], fa, pb);
;   pv_rd<1>(fa, vb0, vb1);
; #pragma unroll
;   for (int r = 1; r < 8; ++r) mx = fmaxf(mx, n0[r]);
;   asm volatile("s_waitcnt lgkmcnt(0)" ::: "memory"); SBAR();
;   pv_mm(o[1], fa, pb);
;   pv_rd<2>(fa, vb0, vb1);
; #pragma unroll
;   for (int r = 8; r < 16; ++r) mx = fmaxf(mx, n0[r]);
;   asm volatile("s_waitcnt lgkmcnt(0)" ::: "memory"); SBAR();
;   pv_mm(o[2], fa, pb);
;   pv_rd<3>(fa, vb0, vb1);
; #pragma unroll
;   for (int r = 0; r < 8; ++r) mx = fmaxf(mx, n1[r]);
;   asm volatile("s_waitcnt lgkmcnt(0)" ::: "memory"); SBAR();
;   pv_mm(o[3], fa, pb);
; #pragma unroll
;   for (int r = 8; r < 16; ++r) mx = fmaxf(mx, n1[r]);
;   pm = mx;
; }
	v_cvt_pk_f16_f32 v85, v220, v221
	v_cvt_pk_f16_f32 v84, v218, v219
	v_cvt_pk_f16_f32 v83, v216, v217
	v_cvt_pk_f16_f32 v82, v214, v215
	s_nop 1
	v_mfma_f32_32x32x16_f16 v[50:65], v[66:69], v[82:85], v[50:65]
	v_cvt_pk_f16_f32 v69, v210, v211
	v_cvt_pk_f16_f32 v68, v208, v209
	v_cvt_pk_f16_f32 v67, v204, v205
	v_cvt_pk_f16_f32 v66, v202, v203
	s_nop 1
	v_mfma_f32_32x32x16_f16 v[50:65], v[70:73], v[66:69], v[50:65]
	v_cvt_pk_f16_f32 v73, v88, v89
	v_cvt_pk_f16_f32 v72, v86, v87
	v_cvt_pk_f16_f32 v71, v196, v197
	v_cvt_pk_f16_f32 v70, v194, v195
	v_max_f32_e32 v194, v115, v115
	v_max_f32_e32 v195, v114, v114
	v_max_f32_e32 v194, v195, v194
	v_mfma_f32_32x32x16_f16 v[50:65], v[74:77], v[70:73], v[50:65]
	v_cvt_pk_f16_f32 v77, v96, v97
	v_cvt_pk_f16_f32 v76, v94, v95
	v_cvt_pk_f16_f32 v75, v92, v93
	v_cvt_pk_f16_f32 v74, v90, v91
	v_max3_f32 v194, v194, v116, v117
	v_max3_f32 v194, v194, v118, v119
	v_max3_f32 v194, v194, v120, v121
	v_mfma_f32_32x32x16_f16 v[50:65], v[78:81], v[74:77], v[50:65]
	ds_read_b64_tr_b16 v[78:79], v198 offset:0x200
	ds_read_b64_tr_b16 v[80:81], v199 offset:0xa00
	ds_read_b64_tr_b16 v[86:87], v198 offset:0x1200
	ds_read_b64_tr_b16 v[88:89], v199 offset:0x1a00
	ds_read_b64_tr_b16 v[90:91], v198 offset:0x2200
	ds_read_b64_tr_b16 v[92:93], v199 offset:0x2a00
	ds_read_b64_tr_b16 v[94:95], v198 offset:0x3200
	ds_read_b64_tr_b16 v[96:97], v199 offset:0x3a00
	s_waitcnt lgkmcnt(0)
	s_nop 0
	v_mfma_f32_32x32x16_f16 v[34:49], v[78:81], v[82:85], v[34:49]
	ds_read_b64_tr_b16 v[78:79], v198 offset:0x400
	ds_read_b64_tr_b16 v[80:81], v199 offset:0xc00
	v_max3_f32 v194, v194, v122, v123
	v_max3_f32 v194, v194, v124, v125
	v_max3_f32 v194, v194, v126, v127
	v_max3_f32 v194, v194, v128, v129
	v_mfma_f32_32x32x16_f16 v[34:49], v[86:89], v[66:69], v[34:49]
	ds_read_b64_tr_b16 v[86:87], v198 offset:0x1400
	ds_read_b64_tr_b16 v[88:89], v199 offset:0x1c00
	v_mfma_f32_32x32x16_f16 v[34:49], v[90:93], v[70:73], v[34:49]
	ds_read_b64_tr_b16 v[90:91], v198 offset:0x2400
	ds_read_b64_tr_b16 v[92:93], v199 offset:0x2c00
	v_mfma_f32_32x32x16_f16 v[34:49], v[94:97], v[74:77], v[34:49]
	ds_read_b64_tr_b16 v[94:95], v198 offset:0x3400
	ds_read_b64_tr_b16 v[96:97], v199 offset:0x3c00
	s_waitcnt lgkmcnt(0)
	v_mfma_f32_32x32x16_f16 v[18:33], v[78:81], v[82:85], v[18:33]
	ds_read_b64_tr_b16 v[78:79], v198 offset:0x600
	ds_read_b64_tr_b16 v[80:81], v199 offset:0xe00
	v_max3_f32 v194, v194, v98, v99
	v_max3_f32 v194, v194, v100, v101
	v_max3_f32 v194, v194, v102, v103
	v_max3_f32 v194, v194, v104, v105
	v_mfma_f32_32x32x16_f16 v[18:33], v[86:89], v[66:69], v[18:33]
	ds_read_b64_tr_b16 v[86:87], v198 offset:0x1600
	ds_read_b64_tr_b16 v[88:89], v199 offset:0x1e00
	v_mfma_f32_32x32x16_f16 v[18:33], v[90:93], v[70:73], v[18:33]
	ds_read_b64_tr_b16 v[90:91], v198 offset:0x2600
	ds_read_b64_tr_b16 v[92:93], v199 offset:0x2e00
	v_mfma_f32_32x32x16_f16 v[18:33], v[94:97], v[74:77], v[18:33]
	ds_read_b64_tr_b16 v[94:95], v198 offset:0x3600
	ds_read_b64_tr_b16 v[96:97], v199 offset:0x3e00
	s_waitcnt lgkmcnt(0)
	v_mfma_f32_32x32x16_f16 v[2:17], v[78:81], v[82:85], v[2:17]
	v_mfma_f32_32x32x16_f16 v[2:17], v[86:89], v[66:69], v[2:17]
	v_max3_f32 v66, v194, v106, v107
	v_max3_f32 v66, v66, v108, v109
	v_max3_f32 v66, v66, v110, v111
	v_max3_f32 v66, v66, v112, v113
	v_mov_b32_e32 v67, v66
	s_nop 1
	v_permlane32_swap_b32_e32 v66, v67
	v_mfma_f32_32x32x16_f16 v[2:17], v[90:93], v[70:73], v[2:17]
	v_max_f32_e32 v67, v67, v67
	v_max_f32_e32 v66, v66, v66
	v_max_f32_e32 v66, v66, v67
	v_sub_f32_e32 v67, v66, v191
	v_cmp_ge_f32_e32 vcc, s73, v67
	s_cmp_eq_u64 vcc, exec
	v_mfma_f32_32x32x16_f16 v[2:17], v[94:97], v[74:77], v[2:17]
	s_cbranch_scc0 .Lresc2
